# P0 RMSNorm loop hand-written: gains hoisted, no per-store vmcnt(0), rows interleaved, next rows prefetched
# speedup vs baseline: 1.0183x; 1.0183x over previous
; __device__ __forceinline__ void rms_rows4_to_bf16(const float* xrow, const float* g, bf16* orow, int lane) {
;     f32x4 v[4][4]; float s[4];
; #pragma unroll
;     for (int r = 0; r < 4; ++r) { const f32x4* xr = (const f32x4*)(xrow + (size_t)r * DM) + lane;
; #pragma unroll
;         for (int j = 0; j < 4; ++j) v[r][j] = __builtin_nontemporal_load(xr + 64 * j); }
; #pragma unroll
;     for (int r = 0; r < 4; ++r) { float t = 0.f;
; #pragma unroll
;         for (int j = 0; j < 4; ++j) t += (v[r][j].x * v[r][j].x + v[r][j].y * v[r][j].y) + (v[r][j].z * v[r][j].z + v[r][j].w * v[r][j].w);
;         s[r] = t; }
; #pragma unroll
;     for (int o = 1; o < 64; o <<= 1) {
; #pragma unroll
;         for (int r = 0; r < 4; ++r) s[r] += __shfl_xor(s[r], o); }
; __global__ void __launch_bounds__(NWAVES * 64, 2) fwd_megakernel(Args a) {
;     ...
;         for (int m = gw * 4; m < M; m += NGW * 4) rms_rows4_to_bf16(a.x + (size_t)m * DM, a.norm_in, XN + (size_t)m * DM, lane);
.LBB0_67:
	v_readlane_b32 s2, v253, 25
	s_cmpk_gt_i32 s2, 0xfff
	v_readlane_b32 s3, v253, 26
	s_cbranch_scc1 .LBB0_70
	v_readlane_b32 s2, v253, 25
	v_readlane_b32 s12, v253, 4
	v_readlane_b32 s13, v253, 5
	v_readlane_b32 s14, v253, 6
	v_readlane_b32 s15, v253, 7
	s_lshl_b32 s20, s2, 2
	s_lshl_b32 s21, s99, 5
	v_lshlrev_b32_e32 v98, 4, v231
	v_lshlrev_b32_e32 v99, 3, v231
	v_xor_b32_e32 v90, 1, v231
	v_lshlrev_b32_e32 v90, 2, v90
	v_xor_b32_e32 v91, 2, v231
	v_lshlrev_b32_e32 v91, 2, v91
	v_xor_b32_e32 v92, 4, v231
	v_lshlrev_b32_e32 v92, 2, v92
	v_xor_b32_e32 v93, 8, v231
	v_lshlrev_b32_e32 v93, 2, v93
	v_xor_b32_e32 v94, 16, v231
	v_lshlrev_b32_e32 v94, 2, v94
	v_xor_b32_e32 v95, 32, v231
	v_lshlrev_b32_e32 v95, 2, v95
	v_mov_b32_e32 v80, 0x3727c5ac
	global_load_dwordx4 v[0:3], v98, s[14:15] offset:0
	global_load_dwordx4 v[4:7], v98, s[14:15] offset:1024
	global_load_dwordx4 v[8:11], v98, s[14:15] offset:2048
	global_load_dwordx4 v[12:15], v98, s[14:15] offset:3072
	s_ashr_i32 s3, s20, 31
	s_mov_b32 s2, s20
	s_lshl_b64 s[2:3], s[2:3], 12
	s_add_u32 s4, s12, s2
	s_addc_u32 s5, s13, s3
	s_add_u32 s6, s4, 0x1000
	s_addc_u32 s7, s5, 0
	s_add_u32 s8, s4, 0x2000
	s_addc_u32 s9, s5, 0
	s_add_u32 s16, s4, 0x3000
	s_addc_u32 s17, s5, 0
	global_load_dwordx4 v[16:19], v98, s[4:5] offset:0 nt
	global_load_dwordx4 v[20:23], v98, s[4:5] offset:1024 nt
	global_load_dwordx4 v[24:27], v98, s[4:5] offset:2048 nt
	global_load_dwordx4 v[28:31], v98, s[4:5] offset:3072 nt
	global_load_dwordx4 v[32:35], v98, s[6:7] offset:0 nt
	global_load_dwordx4 v[36:39], v98, s[6:7] offset:1024 nt
	global_load_dwordx4 v[40:43], v98, s[6:7] offset:2048 nt
	global_load_dwordx4 v[44:47], v98, s[6:7] offset:3072 nt
	global_load_dwordx4 v[48:51], v98, s[8:9] offset:0 nt
	global_load_dwordx4 v[52:55], v98, s[8:9] offset:1024 nt
	global_load_dwordx4 v[56:59], v98, s[8:9] offset:2048 nt
	global_load_dwordx4 v[60:63], v98, s[8:9] offset:3072 nt
	global_load_dwordx4 v[64:67], v98, s[16:17] offset:0 nt
	global_load_dwordx4 v[68:71], v98, s[16:17] offset:1024 nt
	global_load_dwordx4 v[72:75], v98, s[16:17] offset:2048 nt
	global_load_dwordx4 v[76:79], v98, s[16:17] offset:3072 nt
	s_ashr_i32 s3, s20, 31
	s_mov_b32 s2, s20
	s_lshl_b64 s[2:3], s[2:3], 11
	s_add_u32 s18, s96, s2
	s_addc_u32 s19, s97, s3
	s_add_u32 s18, s18, 0x1800000
	s_addc_u32 s19, s19, 0
	s_add_u32 s22, s18, 0x1000
	s_addc_u32 s23, s19, 0
	s_ashr_i32 s3, s21, 31
	s_mov_b32 s2, s21
	s_lshl_b64 s[26:27], s[2:3], 12
	s_lshl_b64 s[2:3], s[2:3], 11
	s_waitcnt vmcnt(12)
	v_pk_mul_f32 v[96:97], v[16:17], v[16:17]
	v_pk_fma_f32 v[96:97], v[18:19], v[18:19], v[96:97]
	v_pk_fma_f32 v[96:97], v[20:21], v[20:21], v[96:97]
	v_pk_fma_f32 v[96:97], v[22:23], v[22:23], v[96:97]
	v_pk_fma_f32 v[96:97], v[24:25], v[24:25], v[96:97]
	v_pk_fma_f32 v[96:97], v[26:27], v[26:27], v[96:97]
	v_pk_fma_f32 v[96:97], v[28:29], v[28:29], v[96:97]
	v_pk_fma_f32 v[96:97], v[30:31], v[30:31], v[96:97]
	v_add_f32_e32 v82, v96, v97
	s_waitcnt vmcnt(8)
	v_pk_mul_f32 v[96:97], v[32:33], v[32:33]
	v_pk_fma_f32 v[96:97], v[34:35], v[34:35], v[96:97]
	v_pk_fma_f32 v[96:97], v[36:37], v[36:37], v[96:97]
	v_pk_fma_f32 v[96:97], v[38:39], v[38:39], v[96:97]
	v_pk_fma_f32 v[96:97], v[40:41], v[40:41], v[96:97]
	v_pk_fma_f32 v[96:97], v[42:43], v[42:43], v[96:97]
	v_pk_fma_f32 v[96:97], v[44:45], v[44:45], v[96:97]
	v_pk_fma_f32 v[96:97], v[46:47], v[46:47], v[96:97]
	v_add_f32_e32 v84, v96, v97
	s_waitcnt vmcnt(4)
	v_pk_mul_f32 v[96:97], v[48:49], v[48:49]
	v_pk_fma_f32 v[96:97], v[50:51], v[50:51], v[96:97]
	v_pk_fma_f32 v[96:97], v[52:53], v[52:53], v[96:97]
	v_pk_fma_f32 v[96:97], v[54:55], v[54:55], v[96:97]
	v_pk_fma_f32 v[96:97], v[56:57], v[56:57], v[96:97]
	v_pk_fma_f32 v[96:97], v[58:59], v[58:59], v[96:97]
	v_pk_fma_f32 v[96:97], v[60:61], v[60:61], v[96:97]
	v_pk_fma_f32 v[96:97], v[62:63], v[62:63], v[96:97]
	v_add_f32_e32 v86, v96, v97
	s_waitcnt vmcnt(0)
	v_pk_mul_f32 v[96:97], v[64:65], v[64:65]
	v_pk_fma_f32 v[96:97], v[66:67], v[66:67], v[96:97]
	v_pk_fma_f32 v[96:97], v[68:69], v[68:69], v[96:97]
	v_pk_fma_f32 v[96:97], v[70:71], v[70:71], v[96:97]
	v_pk_fma_f32 v[96:97], v[72:73], v[72:73], v[96:97]
	v_pk_fma_f32 v[96:97], v[74:75], v[74:75], v[96:97]
	v_pk_fma_f32 v[96:97], v[76:77], v[76:77], v[96:97]
	v_pk_fma_f32 v[96:97], v[78:79], v[78:79], v[96:97]
	v_add_f32_e32 v88, v96, v97
	ds_bpermute_b32 v83, v90, v82
	ds_bpermute_b32 v85, v90, v84
	ds_bpermute_b32 v87, v90, v86
	ds_bpermute_b32 v89, v90, v88
	s_waitcnt lgkmcnt(3)
	v_add_f32_e32 v82, v82, v83
	s_waitcnt lgkmcnt(2)
	v_add_f32_e32 v84, v84, v85
	s_waitcnt lgkmcnt(1)
	v_add_f32_e32 v86, v86, v87
	s_waitcnt lgkmcnt(0)
	v_add_f32_e32 v88, v88, v89
	ds_bpermute_b32 v83, v91, v82
	ds_bpermute_b32 v85, v91, v84
	ds_bpermute_b32 v87, v91, v86
	ds_bpermute_b32 v89, v91, v88
	s_waitcnt lgkmcnt(3)
	v_add_f32_e32 v82, v82, v83
	s_waitcnt lgkmcnt(2)
	v_add_f32_e32 v84, v84, v85
	s_waitcnt lgkmcnt(1)
	v_add_f32_e32 v86, v86, v87
	s_waitcnt lgkmcnt(0)
	v_add_f32_e32 v88, v88, v89
	ds_bpermute_b32 v83, v92, v82
	ds_bpermute_b32 v85, v92, v84
	ds_bpermute_b32 v87, v92, v86
	ds_bpermute_b32 v89, v92, v88
	s_waitcnt lgkmcnt(3)
	v_add_f32_e32 v82, v82, v83
	s_waitcnt lgkmcnt(2)
	v_add_f32_e32 v84, v84, v85
	s_waitcnt lgkmcnt(1)
	v_add_f32_e32 v86, v86, v87
	s_waitcnt lgkmcnt(0)
	v_add_f32_e32 v88, v88, v89
	ds_bpermute_b32 v83, v93, v82
	ds_bpermute_b32 v85, v93, v84
	ds_bpermute_b32 v87, v93, v86
	ds_bpermute_b32 v89, v93, v88
	s_waitcnt lgkmcnt(3)
	v_add_f32_e32 v82, v82, v83
	s_waitcnt lgkmcnt(2)
	v_add_f32_e32 v84, v84, v85
	s_waitcnt lgkmcnt(1)
	v_add_f32_e32 v86, v86, v87
	s_waitcnt lgkmcnt(0)
; __device__ __forceinline__ unsigned pk2(float lo, float hi) { return pg8::cvt_pk_bf16(lo, hi); }
; __device__ __forceinline__ void rms_rows4_to_bf16(const float* xrow, const float* g, bf16* orow, int lane) {
;     ...
;     for (int o = 1; o < 64; o <<= 1) {
; #pragma unroll
;         for (int r = 0; r < 4; ++r) s[r] += __shfl_xor(s[r], o); }
;     const f32x4* gr = (const f32x4*)g + lane;
; #pragma unroll
;     for (int r = 0; r < 4; ++r) { const float rstd = __builtin_amdgcn_rsqf(s[r] * (1.f / DM) + pg8::RMS_EPS);
;         unsigned long long* o8 = (unsigned long long*)(orow + (size_t)r * DM) + lane;
; #pragma unroll
;         for (int j = 0; j < 4; ++j) { const f32x4 y = v[r][j] * rstd * gr[64 * j];
;             o8[64 * j] = (unsigned long long)pk2(y.x, y.y) | ((unsigned long long)pk2(y.z, y.w) << 32); } }
	v_add_f32_e32 v88, v88, v89
	ds_bpermute_b32 v83, v94, v82
	ds_bpermute_b32 v85, v94, v84
	ds_bpermute_b32 v87, v94, v86
	ds_bpermute_b32 v89, v94, v88
	s_waitcnt lgkmcnt(3)
	v_add_f32_e32 v82, v82, v83
	s_waitcnt lgkmcnt(2)
	v_add_f32_e32 v84, v84, v85
	s_waitcnt lgkmcnt(1)
	v_add_f32_e32 v86, v86, v87
	s_waitcnt lgkmcnt(0)
	v_add_f32_e32 v88, v88, v89
	ds_bpermute_b32 v83, v95, v82
	ds_bpermute_b32 v85, v95, v84
	ds_bpermute_b32 v87, v95, v86
	ds_bpermute_b32 v89, v95, v88
	s_waitcnt lgkmcnt(3)
	v_add_f32_e32 v82, v82, v83
	s_waitcnt lgkmcnt(2)
	v_add_f32_e32 v84, v84, v85
	s_waitcnt lgkmcnt(1)
	v_add_f32_e32 v86, v86, v87
	s_waitcnt lgkmcnt(0)
	v_add_f32_e32 v88, v88, v89
	v_fmamk_f32 v82, v82, 0x3a800000, v80
	v_fmamk_f32 v84, v84, 0x3a800000, v80
	v_fmamk_f32 v86, v86, 0x3a800000, v80
	v_fmamk_f32 v88, v88, 0x3a800000, v80
	v_rsq_f32_e32 v82, v82
	v_rsq_f32_e32 v84, v84
	v_rsq_f32_e32 v86, v86
	v_rsq_f32_e32 v88, v88
	s_nop 0
	s_add_i32 s20, s20, s21
	s_cmpk_lt_i32 s20, 0x4000
	s_cselect_b32 s24, 1, 0
	v_pk_mul_f32 v[16:17], v[16:17], v[82:83] op_sel_hi:[1,0]
	v_pk_mul_f32 v[18:19], v[18:19], v[82:83] op_sel_hi:[1,0]
	v_pk_mul_f32 v[16:17], v[0:1], v[16:17]
	v_pk_mul_f32 v[18:19], v[2:3], v[18:19]
	v_cvt_pk_bf16_f32 v16, v16, v17
	v_cvt_pk_bf16_f32 v17, v18, v19
	global_store_dwordx2 v99, v[16:17], s[18:19] offset:0
	v_pk_mul_f32 v[20:21], v[20:21], v[82:83] op_sel_hi:[1,0]
	v_pk_mul_f32 v[22:23], v[22:23], v[82:83] op_sel_hi:[1,0]
	v_pk_mul_f32 v[20:21], v[4:5], v[20:21]
	v_pk_mul_f32 v[22:23], v[6:7], v[22:23]
	v_cvt_pk_bf16_f32 v20, v20, v21
	v_cvt_pk_bf16_f32 v21, v22, v23
	global_store_dwordx2 v99, v[20:21], s[18:19] offset:512
	v_pk_mul_f32 v[24:25], v[24:25], v[82:83] op_sel_hi:[1,0]
	v_pk_mul_f32 v[26:27], v[26:27], v[82:83] op_sel_hi:[1,0]
	v_pk_mul_f32 v[24:25], v[8:9], v[24:25]
	v_pk_mul_f32 v[26:27], v[10:11], v[26:27]
	v_cvt_pk_bf16_f32 v24, v24, v25
	v_cvt_pk_bf16_f32 v25, v26, v27
	global_store_dwordx2 v99, v[24:25], s[18:19] offset:1024
	v_pk_mul_f32 v[28:29], v[28:29], v[82:83] op_sel_hi:[1,0]
	v_pk_mul_f32 v[30:31], v[30:31], v[82:83] op_sel_hi:[1,0]
	v_pk_mul_f32 v[28:29], v[12:13], v[28:29]
	v_pk_mul_f32 v[30:31], v[14:15], v[30:31]
	v_cvt_pk_bf16_f32 v28, v28, v29
	v_cvt_pk_bf16_f32 v29, v30, v31
	global_store_dwordx2 v99, v[28:29], s[18:19] offset:1536
	s_add_u32 s4, s4, s26
	s_addc_u32 s5, s5, s27
	s_cmp_eq_u32 s24, 0
	s_cbranch_scc1 .Lp0_f_np0
	global_load_dwordx4 v[16:19], v98, s[4:5] offset:0 nt
	global_load_dwordx4 v[20:23], v98, s[4:5] offset:1024 nt
	global_load_dwordx4 v[24:27], v98, s[4:5] offset:2048 nt
	global_load_dwordx4 v[28:31], v98, s[4:5] offset:3072 nt
.Lp0_f_np0:
	v_pk_mul_f32 v[32:33], v[32:33], v[84:85] op_sel_hi:[1,0]
	v_pk_mul_f32 v[34:35], v[34:35], v[84:85] op_sel_hi:[1,0]
	v_pk_mul_f32 v[32:33], v[0:1], v[32:33]
	v_pk_mul_f32 v[34:35], v[2:3], v[34:35]
	v_cvt_pk_bf16_f32 v32, v32, v33
	v_cvt_pk_bf16_f32 v33, v34, v35
	global_store_dwordx2 v99, v[32:33], s[18:19] offset:2048
	v_pk_mul_f32 v[36:37], v[36:37], v[84:85] op_sel_hi:[1,0]
	v_pk_mul_f32 v[38:39], v[38:39], v[84:85] op_sel_hi:[1,0]
	v_pk_mul_f32 v[36:37], v[4:5], v[36:37]
	v_pk_mul_f32 v[38:39], v[6:7], v[38:39]
	v_cvt_pk_bf16_f32 v36, v36, v37
	v_cvt_pk_bf16_f32 v37, v38, v39
	global_store_dwordx2 v99, v[36:37], s[18:19] offset:2560
	v_pk_mul_f32 v[40:41], v[40:41], v[84:85] op_sel_hi:[1,0]
	v_pk_mul_f32 v[42:43], v[42:43], v[84:85] op_sel_hi:[1,0]
	v_pk_mul_f32 v[40:41], v[8:9], v[40:41]
	v_pk_mul_f32 v[42:43], v[10:11], v[42:43]
	v_cvt_pk_bf16_f32 v40, v40, v41
	v_cvt_pk_bf16_f32 v41, v42, v43
	global_store_dwordx2 v99, v[40:41], s[18:19] offset:3072
	v_pk_mul_f32 v[44:45], v[44:45], v[84:85] op_sel_hi:[1,0]
	v_pk_mul_f32 v[46:47], v[46:47], v[84:85] op_sel_hi:[1,0]
	v_pk_mul_f32 v[44:45], v[12:13], v[44:45]
	v_pk_mul_f32 v[46:47], v[14:15], v[46:47]
	v_cvt_pk_bf16_f32 v44, v44, v45
	v_cvt_pk_bf16_f32 v45, v46, v47
	global_store_dwordx2 v99, v[44:45], s[18:19] offset:3584
	s_add_u32 s6, s6, s26
	s_addc_u32 s7, s7, s27
	s_cmp_eq_u32 s24, 0
	s_cbranch_scc1 .Lp0_f_np1
	global_load_dwordx4 v[32:35], v98, s[6:7] offset:0 nt
	global_load_dwordx4 v[36:39], v98, s[6:7] offset:1024 nt
	global_load_dwordx4 v[40:43], v98, s[6:7] offset:2048 nt
	global_load_dwordx4 v[44:47], v98, s[6:7] offset:3072 nt
.Lp0_f_np1:
	v_pk_mul_f32 v[48:49], v[48:49], v[86:87] op_sel_hi:[1,0]
	v_pk_mul_f32 v[50:51], v[50:51], v[86:87] op_sel_hi:[1,0]
	v_pk_mul_f32 v[48:49], v[0:1], v[48:49]
	v_pk_mul_f32 v[50:51], v[2:3], v[50:51]
	v_cvt_pk_bf16_f32 v48, v48, v49
	v_cvt_pk_bf16_f32 v49, v50, v51
	global_store_dwordx2 v99, v[48:49], s[22:23] offset:0
	v_pk_mul_f32 v[52:53], v[52:53], v[86:87] op_sel_hi:[1,0]
	v_pk_mul_f32 v[54:55], v[54:55], v[86:87] op_sel_hi:[1,0]
	v_pk_mul_f32 v[52:53], v[4:5], v[52:53]
	v_pk_mul_f32 v[54:55], v[6:7], v[54:55]
	v_cvt_pk_bf16_f32 v52, v52, v53
	v_cvt_pk_bf16_f32 v53, v54, v55
	global_store_dwordx2 v99, v[52:53], s[22:23] offset:512
	v_pk_mul_f32 v[56:57], v[56:57], v[86:87] op_sel_hi:[1,0]
	v_pk_mul_f32 v[58:59], v[58:59], v[86:87] op_sel_hi:[1,0]
	v_pk_mul_f32 v[56:57], v[8:9], v[56:57]
	v_pk_mul_f32 v[58:59], v[10:11], v[58:59]
	v_cvt_pk_bf16_f32 v56, v56, v57
	v_cvt_pk_bf16_f32 v57, v58, v59
	global_store_dwordx2 v99, v[56:57], s[22:23] offset:1024
	v_pk_mul_f32 v[60:61], v[60:61], v[86:87] op_sel_hi:[1,0]
	v_pk_mul_f32 v[62:63], v[62:63], v[86:87] op_sel_hi:[1,0]
	v_pk_mul_f32 v[60:61], v[12:13], v[60:61]
	v_pk_mul_f32 v[62:63], v[14:15], v[62:63]
	v_cvt_pk_bf16_f32 v60, v60, v61
	v_cvt_pk_bf16_f32 v61, v62, v63
	global_store_dwordx2 v99, v[60:61], s[22:23] offset:1536
	s_add_u32 s8, s8, s26
	s_addc_u32 s9, s9, s27
	s_cmp_eq_u32 s24, 0
	s_cbranch_scc1 .Lp0_f_np2
	global_load_dwordx4 v[48:51], v98, s[8:9] offset:0 nt
	global_load_dwordx4 v[52:55], v98, s[8:9] offset:1024 nt
	global_load_dwordx4 v[56:59], v98, s[8:9] offset:2048 nt
	global_load_dwordx4 v[60:63], v98, s[8:9] offset:3072 nt
; __device__ __forceinline__ unsigned pk2(float lo, float hi) { return pg8::cvt_pk_bf16(lo, hi); }
; __device__ __forceinline__ void rms_rows4_to_bf16(const float* xrow, const float* g, bf16* orow, int lane) {
;     ...
;     for (int r = 0; r < 4; ++r) { const float rstd = __builtin_amdgcn_rsqf(s[r] * (1.f / DM) + pg8::RMS_EPS);
;         unsigned long long* o8 = (unsigned long long*)(orow + (size_t)r * DM) + lane;
; #pragma unroll
;         for (int j = 0; j < 4; ++j) { const f32x4 y = v[r][j] * rstd * gr[64 * j];
;             o8[64 * j] = (unsigned long long)pk2(y.x, y.y) | ((unsigned long long)pk2(y.z, y.w) << 32); } }
; __global__ void __launch_bounds__(NWAVES * 64, 2) fwd_megakernel(Args a) {
;     ...
;         for (int m = gw * 4; m < M; m += NGW * 4) rms_rows4_to_bf16(a.x + (size_t)m * DM, a.norm_in, XN + (size_t)m * DM, lane);
.Lp0_f_np2:
	v_pk_mul_f32 v[64:65], v[64:65], v[88:89] op_sel_hi:[1,0]
	v_pk_mul_f32 v[66:67], v[66:67], v[88:89] op_sel_hi:[1,0]
	v_pk_mul_f32 v[64:65], v[0:1], v[64:65]
	v_pk_mul_f32 v[66:67], v[2:3], v[66:67]
	v_cvt_pk_bf16_f32 v64, v64, v65
	v_cvt_pk_bf16_f32 v65, v66, v67
	global_store_dwordx2 v99, v[64:65], s[22:23] offset:2048
	v_pk_mul_f32 v[68:69], v[68:69], v[88:89] op_sel_hi:[1,0]
	v_pk_mul_f32 v[70:71], v[70:71], v[88:89] op_sel_hi:[1,0]
	v_pk_mul_f32 v[68:69], v[4:5], v[68:69]
	v_pk_mul_f32 v[70:71], v[6:7], v[70:71]
	v_cvt_pk_bf16_f32 v68, v68, v69
	v_cvt_pk_bf16_f32 v69, v70, v71
	global_store_dwordx2 v99, v[68:69], s[22:23] offset:2560
	v_pk_mul_f32 v[72:73], v[72:73], v[88:89] op_sel_hi:[1,0]
	v_pk_mul_f32 v[74:75], v[74:75], v[88:89] op_sel_hi:[1,0]
	v_pk_mul_f32 v[72:73], v[8:9], v[72:73]
	v_pk_mul_f32 v[74:75], v[10:11], v[74:75]
	v_cvt_pk_bf16_f32 v72, v72, v73
	v_cvt_pk_bf16_f32 v73, v74, v75
	global_store_dwordx2 v99, v[72:73], s[22:23] offset:3072
	v_pk_mul_f32 v[76:77], v[76:77], v[88:89] op_sel_hi:[1,0]
	v_pk_mul_f32 v[78:79], v[78:79], v[88:89] op_sel_hi:[1,0]
	v_pk_mul_f32 v[76:77], v[12:13], v[76:77]
	v_pk_mul_f32 v[78:79], v[14:15], v[78:79]
	v_cvt_pk_bf16_f32 v76, v76, v77
	v_cvt_pk_bf16_f32 v77, v78, v79
	global_store_dwordx2 v99, v[76:77], s[22:23] offset:3584
	s_add_u32 s16, s16, s26
	s_addc_u32 s17, s17, s27
	s_cmp_eq_u32 s24, 0
	s_cbranch_scc1 .Lp0_f_np3
	global_load_dwordx4 v[64:67], v98, s[16:17] offset:0 nt
	global_load_dwordx4 v[68:71], v98, s[16:17] offset:1024 nt
	global_load_dwordx4 v[72:75], v98, s[16:17] offset:2048 nt
	global_load_dwordx4 v[76:79], v98, s[16:17] offset:3072 nt
.Lp0_f_np3:
	s_add_u32 s18, s18, s2
	s_addc_u32 s19, s19, s3
	s_add_u32 s22, s22, s2
	s_addc_u32 s23, s23, s3
	s_cmp_eq_u32 s24, 0
	s_cbranch_scc1 .LBB0_70
; __device__ __forceinline__ unsigned pk2(float lo, float hi) { return pg8::cvt_pk_bf16(lo, hi); }
; __device__ __forceinline__ void rms_rows4_to_bf16(const float* xrow, const float* g, bf16* orow, int lane) {
;     f32x4 v[4][4]; float s[4];
; #pragma unroll
;     for (int r = 0; r < 4; ++r) { const f32x4* xr = (const f32x4*)(xrow + (size_t)r * DM) + lane;
; #pragma unroll
;         for (int j = 0; j < 4; ++j) v[r][j] = __builtin_nontemporal_load(xr + 64 * j); }
; #pragma unroll
;     for (int r = 0; r < 4; ++r) { float t = 0.f;
; #pragma unroll
;         for (int j = 0; j < 4; ++j) t += (v[r][j].x * v[r][j].x + v[r][j].y * v[r][j].y) + (v[r][j].z * v[r][j].z + v[r][j].w * v[r][j].w);
;         s[r] = t; }
; #pragma unroll
;     for (int o = 1; o < 64; o <<= 1) {
; #pragma unroll
;         for (int r = 0; r < 4; ++r) s[r] += __shfl_xor(s[r], o); }
;     const f32x4* gr = (const f32x4*)g + lane;
; #pragma unroll
;     for (int r = 0; r < 4; ++r) { const float rstd = __builtin_amdgcn_rsqf(s[r] * (1.f / DM) + pg8::RMS_EPS);
;         unsigned long long* o8 = (unsigned long long*)(orow + (size_t)r * DM) + lane;
; #pragma unroll
;         for (int j = 0; j < 4; ++j) { const f32x4 y = v[r][j] * rstd * gr[64 * j];
;             o8[64 * j] = (unsigned long long)pk2(y.x, y.y) | ((unsigned long long)pk2(y.z, y.w) << 32); } }
.Lp0_loop:
	s_waitcnt vmcnt(24)
	v_pk_mul_f32 v[96:97], v[16:17], v[16:17]
	v_pk_fma_f32 v[96:97], v[18:19], v[18:19], v[96:97]
	v_pk_fma_f32 v[96:97], v[20:21], v[20:21], v[96:97]
	v_pk_fma_f32 v[96:97], v[22:23], v[22:23], v[96:97]
	v_pk_fma_f32 v[96:97], v[24:25], v[24:25], v[96:97]
	v_pk_fma_f32 v[96:97], v[26:27], v[26:27], v[96:97]
	v_pk_fma_f32 v[96:97], v[28:29], v[28:29], v[96:97]
	v_pk_fma_f32 v[96:97], v[30:31], v[30:31], v[96:97]
	v_add_f32_e32 v82, v96, v97
	s_waitcnt vmcnt(16)
	v_pk_mul_f32 v[96:97], v[32:33], v[32:33]
	v_pk_fma_f32 v[96:97], v[34:35], v[34:35], v[96:97]
	v_pk_fma_f32 v[96:97], v[36:37], v[36:37], v[96:97]
	v_pk_fma_f32 v[96:97], v[38:39], v[38:39], v[96:97]
	v_pk_fma_f32 v[96:97], v[40:41], v[40:41], v[96:97]
	v_pk_fma_f32 v[96:97], v[42:43], v[42:43], v[96:97]
	v_pk_fma_f32 v[96:97], v[44:45], v[44:45], v[96:97]
	v_pk_fma_f32 v[96:97], v[46:47], v[46:47], v[96:97]
	v_add_f32_e32 v84, v96, v97
	s_waitcnt vmcnt(8)
	v_pk_mul_f32 v[96:97], v[48:49], v[48:49]
	v_pk_fma_f32 v[96:97], v[50:51], v[50:51], v[96:97]
	v_pk_fma_f32 v[96:97], v[52:53], v[52:53], v[96:97]
	v_pk_fma_f32 v[96:97], v[54:55], v[54:55], v[96:97]
	v_pk_fma_f32 v[96:97], v[56:57], v[56:57], v[96:97]
	v_pk_fma_f32 v[96:97], v[58:59], v[58:59], v[96:97]
	v_pk_fma_f32 v[96:97], v[60:61], v[60:61], v[96:97]
	v_pk_fma_f32 v[96:97], v[62:63], v[62:63], v[96:97]
	v_add_f32_e32 v86, v96, v97
	s_waitcnt vmcnt(0)
	v_pk_mul_f32 v[96:97], v[64:65], v[64:65]
	v_pk_fma_f32 v[96:97], v[66:67], v[66:67], v[96:97]
	v_pk_fma_f32 v[96:97], v[68:69], v[68:69], v[96:97]
	v_pk_fma_f32 v[96:97], v[70:71], v[70:71], v[96:97]
	v_pk_fma_f32 v[96:97], v[72:73], v[72:73], v[96:97]
	v_pk_fma_f32 v[96:97], v[74:75], v[74:75], v[96:97]
	v_pk_fma_f32 v[96:97], v[76:77], v[76:77], v[96:97]
	v_pk_fma_f32 v[96:97], v[78:79], v[78:79], v[96:97]
	v_add_f32_e32 v88, v96, v97
	ds_bpermute_b32 v83, v90, v82
	ds_bpermute_b32 v85, v90, v84
	ds_bpermute_b32 v87, v90, v86
	ds_bpermute_b32 v89, v90, v88
	s_waitcnt lgkmcnt(3)
	v_add_f32_e32 v82, v82, v83
	s_waitcnt lgkmcnt(2)
	v_add_f32_e32 v84, v84, v85
	s_waitcnt lgkmcnt(1)
	v_add_f32_e32 v86, v86, v87
	s_waitcnt lgkmcnt(0)
	v_add_f32_e32 v88, v88, v89
	ds_bpermute_b32 v83, v91, v82
	ds_bpermute_b32 v85, v91, v84
	ds_bpermute_b32 v87, v91, v86
	ds_bpermute_b32 v89, v91, v88
	s_waitcnt lgkmcnt(3)
	v_add_f32_e32 v82, v82, v83
	s_waitcnt lgkmcnt(2)
	v_add_f32_e32 v84, v84, v85
	s_waitcnt lgkmcnt(1)
	v_add_f32_e32 v86, v86, v87
	s_waitcnt lgkmcnt(0)
	v_add_f32_e32 v88, v88, v89
	ds_bpermute_b32 v83, v92, v82
	ds_bpermute_b32 v85, v92, v84
	ds_bpermute_b32 v87, v92, v86
	ds_bpermute_b32 v89, v92, v88
	s_waitcnt lgkmcnt(3)
	v_add_f32_e32 v82, v82, v83
	s_waitcnt lgkmcnt(2)
	v_add_f32_e32 v84, v84, v85
	s_waitcnt lgkmcnt(1)
	v_add_f32_e32 v86, v86, v87
	s_waitcnt lgkmcnt(0)
	v_add_f32_e32 v88, v88, v89
	ds_bpermute_b32 v83, v93, v82
	ds_bpermute_b32 v85, v93, v84
	ds_bpermute_b32 v87, v93, v86
	ds_bpermute_b32 v89, v93, v88
	s_waitcnt lgkmcnt(3)
	v_add_f32_e32 v82, v82, v83
	s_waitcnt lgkmcnt(2)
	v_add_f32_e32 v84, v84, v85
	s_waitcnt lgkmcnt(1)
	v_add_f32_e32 v86, v86, v87
	s_waitcnt lgkmcnt(0)
	v_add_f32_e32 v88, v88, v89
	ds_bpermute_b32 v83, v94, v82
	ds_bpermute_b32 v85, v94, v84
	ds_bpermute_b32 v87, v94, v86
	ds_bpermute_b32 v89, v94, v88
	s_waitcnt lgkmcnt(3)
	v_add_f32_e32 v82, v82, v83
	s_waitcnt lgkmcnt(2)
	v_add_f32_e32 v84, v84, v85
	s_waitcnt lgkmcnt(1)
	v_add_f32_e32 v86, v86, v87
	s_waitcnt lgkmcnt(0)
	v_add_f32_e32 v88, v88, v89
	ds_bpermute_b32 v83, v95, v82
	ds_bpermute_b32 v85, v95, v84
	ds_bpermute_b32 v87, v95, v86
	ds_bpermute_b32 v89, v95, v88
	s_waitcnt lgkmcnt(3)
	v_add_f32_e32 v82, v82, v83
	s_waitcnt lgkmcnt(2)
	v_add_f32_e32 v84, v84, v85
	s_waitcnt lgkmcnt(1)
	v_add_f32_e32 v86, v86, v87
	s_waitcnt lgkmcnt(0)
	v_add_f32_e32 v88, v88, v89
	v_fmamk_f32 v82, v82, 0x3a800000, v80
	v_fmamk_f32 v84, v84, 0x3a800000, v80
	v_fmamk_f32 v86, v86, 0x3a800000, v80
	v_fmamk_f32 v88, v88, 0x3a800000, v80
	v_rsq_f32_e32 v82, v82
	v_rsq_f32_e32 v84, v84
	v_rsq_f32_e32 v86, v86
	v_rsq_f32_e32 v88, v88
	s_nop 0
	s_add_i32 s20, s20, s21
	s_cmpk_lt_i32 s20, 0x4000
	s_cselect_b32 s24, 1, 0
	v_pk_mul_f32 v[16:17], v[16:17], v[82:83] op_sel_hi:[1,0]
	v_pk_mul_f32 v[18:19], v[18:19], v[82:83] op_sel_hi:[1,0]
	v_pk_mul_f32 v[16:17], v[0:1], v[16:17]
	v_pk_mul_f32 v[18:19], v[2:3], v[18:19]
	v_cvt_pk_bf16_f32 v16, v16, v17
	v_cvt_pk_bf16_f32 v17, v18, v19
	global_store_dwordx2 v99, v[16:17], s[18:19] offset:0
	v_pk_mul_f32 v[20:21], v[20:21], v[82:83] op_sel_hi:[1,0]
	v_pk_mul_f32 v[22:23], v[22:23], v[82:83] op_sel_hi:[1,0]
	v_pk_mul_f32 v[20:21], v[4:5], v[20:21]
	v_pk_mul_f32 v[22:23], v[6:7], v[22:23]
	v_cvt_pk_bf16_f32 v20, v20, v21
	v_cvt_pk_bf16_f32 v21, v22, v23
	global_store_dwordx2 v99, v[20:21], s[18:19] offset:512
	v_pk_mul_f32 v[24:25], v[24:25], v[82:83] op_sel_hi:[1,0]
	v_pk_mul_f32 v[26:27], v[26:27], v[82:83] op_sel_hi:[1,0]
	v_pk_mul_f32 v[24:25], v[8:9], v[24:25]
	v_pk_mul_f32 v[26:27], v[10:11], v[26:27]
	v_cvt_pk_bf16_f32 v24, v24, v25
	v_cvt_pk_bf16_f32 v25, v26, v27
	global_store_dwordx2 v99, v[24:25], s[18:19] offset:1024
	v_pk_mul_f32 v[28:29], v[28:29], v[82:83] op_sel_hi:[1,0]
	v_pk_mul_f32 v[30:31], v[30:31], v[82:83] op_sel_hi:[1,0]
	v_pk_mul_f32 v[28:29], v[12:13], v[28:29]
	v_pk_mul_f32 v[30:31], v[14:15], v[30:31]
	v_cvt_pk_bf16_f32 v28, v28, v29
	v_cvt_pk_bf16_f32 v29, v30, v31
	global_store_dwordx2 v99, v[28:29], s[18:19] offset:1536
	s_add_u32 s4, s4, s26
	s_addc_u32 s5, s5, s27
	s_cmp_eq_u32 s24, 0
	s_cbranch_scc1 .Lp0_s_np0
	global_load_dwordx4 v[16:19], v98, s[4:5] offset:0 nt
	global_load_dwordx4 v[20:23], v98, s[4:5] offset:1024 nt
	global_load_dwordx4 v[24:27], v98, s[4:5] offset:2048 nt
	global_load_dwordx4 v[28:31], v98, s[4:5] offset:3072 nt

; __global__ void __launch_bounds__(NWAVES * 64, 2) fwd_megakernel(Args a) {
;     ...
;         for (int m = gw * 4; m < M; m += NGW * 4) rms_rows4_to_bf16(a.x + (size_t)m * DM, a.norm_in, XN + (size_t)m * DM, lane);
.Lp0_s_np3:
	s_add_u32 s18, s18, s2
	s_addc_u32 s19, s19, s3
	s_add_u32 s22, s22, s2
	s_addc_u32 s23, s23, s3
	s_cmp_eq_u32 s24, 0
	s_cbranch_scc0 .Lp0_loop
